# GU GEMM: MFMA operands swapped (weights as SrcA, activations as SrcB) with permuted weight-column to MFMA-row mapping so each lane holds 8 consecutive output columns of one token; no accumulator re-la
# speedup vs baseline: 1.0177x; 1.0177x over previous
.LBB0_1031:
	s_mul_hi_i32 s0, s2, 0x2e8ba2e9
	s_lshr_b32 s1, s0, 31
	s_ashr_i32 s0, s0, 6
	s_add_i32 s0, s0, s1
	s_lshl_b32 s1, s0, 3
	s_sub_i32 s7, s25, s1
	s_min_i32 s7, s7, 8
	s_abs_i32 s8, s7
	v_cvt_f32_u32_e32 v0, s8
	s_sub_i32 s11, 0, s8
	s_mulk_i32 s0, 0xfea0
	s_add_i32 s9, s0, s2
	v_rcp_iflag_f32_e32 v0, v0
	s_abs_i32 s0, s9
	s_xor_b32 s10, s9, s7
	s_ashr_i32 s10, s10, 31
	v_mul_f32_e32 v0, 0x4f7ffffe, v0
	v_cvt_u32_f32_e32 v0, v0
	v_mov_b32_e32 v237, v179
	v_readfirstlane_b32 s12, v0
	s_mul_i32 s11, s11, s12
	s_mul_hi_u32 s11, s12, s11
	s_add_i32 s12, s12, s11
	s_mul_hi_u32 s11, s0, s12
	s_mul_i32 s12, s11, s8
	s_sub_i32 s0, s0, s12
	s_add_i32 s13, s11, 1
	s_sub_i32 s12, s0, s8
	s_cmp_ge_u32 s0, s8
	s_cselect_b32 s11, s13, s11
	s_cselect_b32 s0, s12, s0
	s_add_i32 s12, s11, 1
	s_cmp_ge_u32 s0, s8
	s_cselect_b32 s0, s12, s11
	s_xor_b32 s0, s0, s10
	s_sub_i32 s0, s0, s10
	s_mul_i32 s7, s7, s0
	s_sub_i32 s7, s9, s7
	s_add_i32 s1, s1, s6
	v_ashrrev_i32_e32 v238, 6, v237
	s_add_i32 s7, s1, s7
	v_lshlrev_b32_e32 v0, 1, v238
	v_lshl_add_u32 v0, s7, 3, v0
	v_ashrrev_i32_e32 v1, 31, v0
	v_bfe_u32 v183, v237, 5, 1
	v_lshlrev_b64 v[0:1], 16, v[0:1]
	v_and_b32_e32 v239, 31, v237
	v_lshl_add_u64 v[0:1], s[64:65], 0, v[0:1]
	v_lshlrev_b32_e32 v176, 9, v183
	s_ashr_i32 s1, s0, 31
	v_lshl_add_u64 v[0:1], v[0:1], 0, v[176:177]
	v_lshlrev_b32_e32 v176, 4, v239
	v_ashrrev_i32_e32 v38, 2, v237
	s_lshl_b64 s[8:9], s[0:1], 18
	v_lshl_add_u64 v[184:185], v[0:1], 0, v[176:177]
	s_add_u32 s8, s4, s8
	v_lshlrev_b32_e32 v0, 5, v38
	v_lshlrev_b32_e32 v2, 3, v237
	s_addc_u32 s9, s5, s9
	v_ashrrev_i32_e32 v1, 31, v0
	v_and_b32_e32 v181, 24, v2
	v_lshl_add_u64 v[0:1], v[0:1], 1, s[8:9]
	v_lshlrev_b32_e32 v176, 1, v181
	v_lshl_add_u64 v[186:187], v[0:1], 0, v[176:177]
	s_movk_i32 s1, 0x2000
	v_add_co_u32_e32 v34, vcc, s1, v186
	v_mul_u32_u24_e32 v36, 40, v239
	s_nop 0
	v_addc_co_u32_e32 v35, vcc, 0, v187, vcc
	v_lshlrev_b32_e32 v37, 4, v183
	v_lshl_add_u32 v241, v36, 1, v37
	v_add_co_u32_e32 v36, vcc, s41, v184
	s_movk_i32 s8, 0x50
	s_nop 0
	v_addc_co_u32_e32 v37, vcc, 0, v185, vcc
	v_mad_u64_u32 v[188:189], s[8:9], v38, s8, v[176:177]
	v_and_b32_e32 v240, 63, v237
	v_bfe_u32 v247, v237, 4, 2
	v_lshlrev_b32_e32 v247, 1, v247
	v_mov_b32_e32 v176, 0x78
	v_lshrrev_b32_e32 v247, v247, v176
	v_and_b32_e32 v247, 3, v247
	v_and_b32_e32 v246, 3, v237
	v_xor_b32_e32 v247, v247, v246
	v_lshlrev_b32_e32 v247, 4, v247
	v_and_b32_e32 v188, 0xffffffcf, v186
	v_or_b32_e32 v188, v188, v247
	v_mov_b32_e32 v189, v187
	v_lshrrev_b32_e32 v176, 6, v237
	v_lshlrev_b32_e32 v247, 11, v176
	v_lshlrev_b32_e32 v176, 10, v176
	v_lshl_add_u64 v[188:189], v[188:189], 0, v[176:177]
	v_readfirstlane_b32 vcc_lo, v247
	v_bfe_u32 v247, v237, 4, 1
	v_lshlrev_b32_e32 v176, 9, v183
	v_lshl_add_u32 v176, v247, 8, v176
	v_lshl_add_u64 v[184:185], v[184:185], 0, v[176:177]
	v_mov_b32_e32 v176, s41
	v_lshl_add_u64 v[186:187], v[184:185], 0, v[176:177]
	v_mov_b32_e32 v176, 0x78
	v_bfe_u32 v247, v237, 2, 1
	v_lshlrev_b32_e32 v247, 2, v247
	v_lshrrev_b32_e32 v247, v247, v176
	v_and_b32_e32 v247, 3, v247
	v_bfe_u32 v246, v237, 4, 2
	v_xor_b32_e32 v247, v247, v246
	v_lshlrev_b32_e32 v247, 4, v247
	v_bfe_u32 v246, v237, 2, 2
	v_lshlrev_b32_e32 v246, 3, v246
	v_and_b32_e32 v162, 3, v237
	v_add_u32_e32 v246, v246, v162
	v_lshl_add_u32 v246, v246, 6, v247
	v_bfe_u32 v247, v237, 2, 1
	v_lshlrev_b32_e32 v247, 2, v247
	v_add_u32_e32 v247, 2, v247
	v_lshrrev_b32_e32 v247, v247, v176
	v_and_b32_e32 v247, 3, v247
	v_bfe_u32 v162, v237, 4, 2
	v_xor_b32_e32 v247, v247, v162
	v_lshlrev_b32_e32 v247, 4, v247
	v_and_b32_e32 v162, 0xffffffcf, v246
	v_add_u32_e32 v162, 0x100, v162
	v_or_b32_e32 v162, v162, v247
	s_mov_b32 s96, 0
	s_mov_b32 m0, vcc_lo
	v_lshl_add_u64 v[160:161], v[188:189], 0, s[96:97]
	global_load_lds_dwordx4 v[160:161], off
	global_load_lds_dwordx4 v[160:161], off offset:1024
	s_mov_b32 s96, 0
	v_lshl_add_u64 v[248:249], v[184:185], 0, s[96:97]
	v_lshl_add_u64 v[250:251], v[186:187], 0, s[96:97]
	global_load_dwordx4 v[128:131], v[248:249], off
	global_load_dwordx4 v[132:135], v[248:249], off offset:256
	global_load_dwordx4 v[136:139], v[250:251], off
	global_load_dwordx4 v[140:143], v[250:251], off offset:256
	s_movk_i32 s96, 0x2000
	s_add_i32 m0, vcc_lo, 8192
	v_lshl_add_u64 v[160:161], v[188:189], 0, s[96:97]
	global_load_lds_dwordx4 v[160:161], off
	global_load_lds_dwordx4 v[160:161], off offset:1024
	s_movk_i32 s96, 0x800
	v_lshl_add_u64 v[248:249], v[184:185], 0, s[96:97]
	v_lshl_add_u64 v[250:251], v[186:187], 0, s[96:97]
	global_load_dwordx4 v[144:147], v[248:249], off
	global_load_dwordx4 v[148:151], v[248:249], off offset:256
	global_load_dwordx4 v[152:155], v[250:251], off
	global_load_dwordx4 v[156:159], v[250:251], off offset:256
	v_mov_b32_e32 v0, 0
	v_mov_b32_e32 v1, 0
	v_mov_b32_e32 v2, 0
	v_mov_b32_e32 v3, 0
	v_mov_b32_e32 v4, 0
	v_mov_b32_e32 v5, 0
	v_mov_b32_e32 v6, 0
	v_mov_b32_e32 v7, 0
	v_mov_b32_e32 v8, 0
	v_mov_b32_e32 v9, 0
	v_mov_b32_e32 v10, 0
	v_mov_b32_e32 v11, 0
	v_mov_b32_e32 v12, 0
	v_mov_b32_e32 v13, 0
	v_mov_b32_e32 v14, 0
	v_mov_b32_e32 v15, 0
	v_mov_b32_e32 v16, 0
	v_mov_b32_e32 v17, 0
	v_mov_b32_e32 v18, 0
	v_mov_b32_e32 v19, 0
	v_mov_b32_e32 v20, 0
	v_mov_b32_e32 v21, 0
	v_mov_b32_e32 v22, 0
	v_mov_b32_e32 v23, 0
	v_mov_b32_e32 v24, 0
	v_mov_b32_e32 v25, 0
	v_mov_b32_e32 v26, 0
	v_mov_b32_e32 v27, 0
	v_mov_b32_e32 v28, 0
	v_mov_b32_e32 v29, 0
	v_mov_b32_e32 v30, 0
	v_mov_b32_e32 v31, 0
	v_mov_b32_e32 v32, 0
	v_mov_b32_e32 v33, 0
	v_mov_b32_e32 v34, 0
	v_mov_b32_e32 v35, 0
	v_mov_b32_e32 v36, 0
	v_mov_b32_e32 v37, 0
	v_mov_b32_e32 v38, 0
	v_mov_b32_e32 v39, 0
	v_mov_b32_e32 v40, 0
	v_mov_b32_e32 v41, 0
	v_mov_b32_e32 v42, 0
	v_mov_b32_e32 v43, 0
	v_mov_b32_e32 v44, 0
	v_mov_b32_e32 v45, 0
	v_mov_b32_e32 v46, 0
	v_mov_b32_e32 v47, 0
	v_mov_b32_e32 v48, 0
	v_mov_b32_e32 v49, 0
	v_mov_b32_e32 v50, 0
	v_mov_b32_e32 v51, 0
	v_mov_b32_e32 v52, 0
	v_mov_b32_e32 v53, 0
	v_mov_b32_e32 v54, 0
	v_mov_b32_e32 v55, 0
	v_mov_b32_e32 v56, 0
	v_mov_b32_e32 v57, 0
	v_mov_b32_e32 v58, 0
	v_mov_b32_e32 v59, 0
	v_mov_b32_e32 v60, 0
	v_mov_b32_e32 v61, 0
	v_mov_b32_e32 v62, 0
	v_mov_b32_e32 v63, 0
	v_mov_b32_e32 v64, 0
	v_mov_b32_e32 v65, 0
	v_mov_b32_e32 v66, 0
	v_mov_b32_e32 v67, 0
	v_mov_b32_e32 v68, 0
	v_mov_b32_e32 v69, 0
	v_mov_b32_e32 v70, 0
	v_mov_b32_e32 v71, 0
	v_mov_b32_e32 v72, 0
	v_mov_b32_e32 v73, 0
	v_mov_b32_e32 v74, 0
	v_mov_b32_e32 v75, 0
	v_mov_b32_e32 v76, 0
	v_mov_b32_e32 v77, 0
	v_mov_b32_e32 v78, 0
	v_mov_b32_e32 v79, 0
	v_mov_b32_e32 v80, 0
	v_mov_b32_e32 v81, 0
	v_mov_b32_e32 v82, 0
	v_mov_b32_e32 v83, 0
	v_mov_b32_e32 v84, 0
	v_mov_b32_e32 v85, 0
	v_mov_b32_e32 v86, 0
	v_mov_b32_e32 v87, 0
	v_mov_b32_e32 v88, 0
	v_mov_b32_e32 v89, 0
	v_mov_b32_e32 v90, 0
	v_mov_b32_e32 v91, 0
	v_mov_b32_e32 v92, 0
	v_mov_b32_e32 v93, 0
	v_mov_b32_e32 v94, 0
	v_mov_b32_e32 v95, 0
	v_mov_b32_e32 v96, 0
	v_mov_b32_e32 v97, 0
	v_mov_b32_e32 v98, 0
	v_mov_b32_e32 v99, 0
	v_mov_b32_e32 v100, 0
	v_mov_b32_e32 v101, 0
	v_mov_b32_e32 v102, 0
	v_mov_b32_e32 v103, 0
	v_mov_b32_e32 v104, 0
	v_mov_b32_e32 v105, 0
	v_mov_b32_e32 v106, 0
	v_mov_b32_e32 v107, 0
	v_mov_b32_e32 v108, 0
	v_mov_b32_e32 v109, 0
	v_mov_b32_e32 v110, 0
	v_mov_b32_e32 v111, 0
	v_mov_b32_e32 v112, 0
	v_mov_b32_e32 v113, 0
	v_mov_b32_e32 v114, 0
	v_mov_b32_e32 v115, 0
	v_mov_b32_e32 v116, 0
	v_mov_b32_e32 v117, 0
	v_mov_b32_e32 v118, 0
	v_mov_b32_e32 v119, 0
	v_mov_b32_e32 v120, 0
	v_mov_b32_e32 v121, 0
	v_mov_b32_e32 v122, 0
	v_mov_b32_e32 v123, 0
	v_mov_b32_e32 v124, 0
	v_mov_b32_e32 v125, 0
	v_mov_b32_e32 v126, 0
	v_mov_b32_e32 v127, 0
	s_mov_b32 s1, 0
	s_waitcnt vmcnt(4)
	s_barrier
.Lg16_gu_k:
	s_add_i32 s8, s1, 2
	s_lshl_b32 s96, s8, 13
	s_add_i32 m0, vcc_lo, 16384
	v_lshl_add_u64 v[160:161], v[188:189], 0, s[96:97]
	global_load_lds_dwordx4 v[160:161], off
	global_load_lds_dwordx4 v[160:161], off offset:1024
	ds_read_b128 v[196:199], v246 offset:0
	ds_read_b128 v[200:203], v162 offset:0
	ds_read_b128 v[204:207], v246 offset:2048
	ds_read_b128 v[242:245], v162 offset:2048
	s_add_i32 s8, s1, 2
	s_lshl_b32 s96, s8, 11
	v_lshl_add_u64 v[248:249], v[184:185], 0, s[96:97]
	v_lshl_add_u64 v[250:251], v[186:187], 0, s[96:97]
	s_waitcnt vmcnt(8) lgkmcnt(3)
	v_mfma_f32_16x16x32_bf16 v[112:115], v[196:199], v[128:131], v[112:115]
	v_mfma_f32_16x16x32_bf16 v[120:123], v[196:199], v[132:135], v[120:123]
	v_mfma_f32_16x16x32_bf16 v[80:83], v[196:199], v[136:139], v[80:83]
	v_mfma_f32_16x16x32_bf16 v[88:91], v[196:199], v[140:143], v[88:91]
	ds_read_b128 v[196:199], v246 offset:4096
	s_waitcnt lgkmcnt(3)
	v_mfma_f32_16x16x32_bf16 v[116:119], v[200:203], v[128:131], v[116:119]
	v_mfma_f32_16x16x32_bf16 v[124:127], v[200:203], v[132:135], v[124:127]
	v_mfma_f32_16x16x32_bf16 v[84:87], v[200:203], v[136:139], v[84:87]
	v_mfma_f32_16x16x32_bf16 v[92:95], v[200:203], v[140:143], v[92:95]
	ds_read_b128 v[200:203], v162 offset:4096
	s_waitcnt lgkmcnt(3)
	v_mfma_f32_16x16x32_bf16 v[96:99], v[204:207], v[128:131], v[96:99]
	v_mfma_f32_16x16x32_bf16 v[104:107], v[204:207], v[132:135], v[104:107]
	v_mfma_f32_16x16x32_bf16 v[64:67], v[204:207], v[136:139], v[64:67]
	v_mfma_f32_16x16x32_bf16 v[72:75], v[204:207], v[140:143], v[72:75]
	ds_read_b128 v[204:207], v246 offset:6144
	s_waitcnt lgkmcnt(3)
	v_mfma_f32_16x16x32_bf16 v[100:103], v[242:245], v[128:131], v[100:103]
	v_mfma_f32_16x16x32_bf16 v[108:111], v[242:245], v[132:135], v[108:111]
	v_mfma_f32_16x16x32_bf16 v[68:71], v[242:245], v[136:139], v[68:71]
	v_mfma_f32_16x16x32_bf16 v[76:79], v[242:245], v[140:143], v[76:79]
	ds_read_b128 v[242:245], v162 offset:6144
	s_waitcnt lgkmcnt(3)
	v_mfma_f32_16x16x32_bf16 v[48:51], v[196:199], v[128:131], v[48:51]
	v_mfma_f32_16x16x32_bf16 v[56:59], v[196:199], v[132:135], v[56:59]
	v_mfma_f32_16x16x32_bf16 v[16:19], v[196:199], v[136:139], v[16:19]
	v_mfma_f32_16x16x32_bf16 v[24:27], v[196:199], v[140:143], v[24:27]
	s_waitcnt lgkmcnt(2)
	v_mfma_f32_16x16x32_bf16 v[52:55], v[200:203], v[128:131], v[52:55]
	v_mfma_f32_16x16x32_bf16 v[60:63], v[200:203], v[132:135], v[60:63]
	v_mfma_f32_16x16x32_bf16 v[20:23], v[200:203], v[136:139], v[20:23]
	v_mfma_f32_16x16x32_bf16 v[28:31], v[200:203], v[140:143], v[28:31]
	s_waitcnt lgkmcnt(1)
	v_mfma_f32_16x16x32_bf16 v[32:35], v[204:207], v[128:131], v[32:35]
	v_mfma_f32_16x16x32_bf16 v[40:43], v[204:207], v[132:135], v[40:43]
	v_mfma_f32_16x16x32_bf16 v[0:3], v[204:207], v[136:139], v[0:3]
	v_mfma_f32_16x16x32_bf16 v[8:11], v[204:207], v[140:143], v[8:11]
	s_waitcnt lgkmcnt(0)
	v_mfma_f32_16x16x32_bf16 v[36:39], v[242:245], v[128:131], v[36:39]
	v_mfma_f32_16x16x32_bf16 v[44:47], v[242:245], v[132:135], v[44:47]
	v_mfma_f32_16x16x32_bf16 v[4:7], v[242:245], v[136:139], v[4:7]
	v_mfma_f32_16x16x32_bf16 v[12:15], v[242:245], v[140:143], v[12:15]
	global_load_dwordx4 v[128:131], v[248:249], off
	global_load_dwordx4 v[132:135], v[248:249], off offset:256
	global_load_dwordx4 v[136:139], v[250:251], off
	global_load_dwordx4 v[140:143], v[250:251], off offset:256
	s_waitcnt vmcnt(10)
	s_barrier
	s_add_i32 s8, s1, 3
	s_lshl_b32 s96, s8, 13
	s_mov_b32 m0, vcc_lo
	v_lshl_add_u64 v[160:161], v[188:189], 0, s[96:97]
	global_load_lds_dwordx4 v[160:161], off
	global_load_lds_dwordx4 v[160:161], off offset:1024
	ds_read_b128 v[196:199], v246 offset:8192
	ds_read_b128 v[200:203], v162 offset:8192
	ds_read_b128 v[204:207], v246 offset:10240
	ds_read_b128 v[242:245], v162 offset:10240
	s_add_i32 s8, s1, 3
	s_lshl_b32 s96, s8, 11
	v_lshl_add_u64 v[248:249], v[184:185], 0, s[96:97]
	v_lshl_add_u64 v[250:251], v[186:187], 0, s[96:97]
	s_waitcnt vmcnt(8) lgkmcnt(3)
	v_mfma_f32_16x16x32_bf16 v[112:115], v[196:199], v[144:147], v[112:115]
	v_mfma_f32_16x16x32_bf16 v[120:123], v[196:199], v[148:151], v[120:123]
	v_mfma_f32_16x16x32_bf16 v[80:83], v[196:199], v[152:155], v[80:83]
	v_mfma_f32_16x16x32_bf16 v[88:91], v[196:199], v[156:159], v[88:91]
	ds_read_b128 v[196:199], v246 offset:12288
	s_waitcnt lgkmcnt(3)
	v_mfma_f32_16x16x32_bf16 v[116:119], v[200:203], v[144:147], v[116:119]
	v_mfma_f32_16x16x32_bf16 v[124:127], v[200:203], v[148:151], v[124:127]
	v_mfma_f32_16x16x32_bf16 v[84:87], v[200:203], v[152:155], v[84:87]
	v_mfma_f32_16x16x32_bf16 v[92:95], v[200:203], v[156:159], v[92:95]
	ds_read_b128 v[200:203], v162 offset:12288
	s_waitcnt lgkmcnt(3)
	v_mfma_f32_16x16x32_bf16 v[96:99], v[204:207], v[144:147], v[96:99]
	v_mfma_f32_16x16x32_bf16 v[104:107], v[204:207], v[148:151], v[104:107]
	v_mfma_f32_16x16x32_bf16 v[64:67], v[204:207], v[152:155], v[64:67]
	v_mfma_f32_16x16x32_bf16 v[72:75], v[204:207], v[156:159], v[72:75]
	ds_read_b128 v[204:207], v246 offset:14336
	s_waitcnt lgkmcnt(3)
	v_mfma_f32_16x16x32_bf16 v[100:103], v[242:245], v[144:147], v[100:103]
	v_mfma_f32_16x16x32_bf16 v[108:111], v[242:245], v[148:151], v[108:111]
	v_mfma_f32_16x16x32_bf16 v[68:71], v[242:245], v[152:155], v[68:71]
	v_mfma_f32_16x16x32_bf16 v[76:79], v[242:245], v[156:159], v[76:79]
	ds_read_b128 v[242:245], v162 offset:14336
	s_waitcnt lgkmcnt(3)
	v_mfma_f32_16x16x32_bf16 v[48:51], v[196:199], v[144:147], v[48:51]
	v_mfma_f32_16x16x32_bf16 v[56:59], v[196:199], v[148:151], v[56:59]
	v_mfma_f32_16x16x32_bf16 v[16:19], v[196:199], v[152:155], v[16:19]
	v_mfma_f32_16x16x32_bf16 v[24:27], v[196:199], v[156:159], v[24:27]
	s_waitcnt lgkmcnt(2)
	v_mfma_f32_16x16x32_bf16 v[52:55], v[200:203], v[144:147], v[52:55]
	v_mfma_f32_16x16x32_bf16 v[60:63], v[200:203], v[148:151], v[60:63]
	v_mfma_f32_16x16x32_bf16 v[20:23], v[200:203], v[152:155], v[20:23]
	v_mfma_f32_16x16x32_bf16 v[28:31], v[200:203], v[156:159], v[28:31]
	s_waitcnt lgkmcnt(1)
	v_mfma_f32_16x16x32_bf16 v[32:35], v[204:207], v[144:147], v[32:35]
	v_mfma_f32_16x16x32_bf16 v[40:43], v[204:207], v[148:151], v[40:43]
	v_mfma_f32_16x16x32_bf16 v[0:3], v[204:207], v[152:155], v[0:3]
	v_mfma_f32_16x16x32_bf16 v[8:11], v[204:207], v[156:159], v[8:11]
	s_waitcnt lgkmcnt(0)
	v_mfma_f32_16x16x32_bf16 v[36:39], v[242:245], v[144:147], v[36:39]
	v_mfma_f32_16x16x32_bf16 v[44:47], v[242:245], v[148:151], v[44:47]
	v_mfma_f32_16x16x32_bf16 v[4:7], v[242:245], v[152:155], v[4:7]
	v_mfma_f32_16x16x32_bf16 v[12:15], v[242:245], v[156:159], v[12:15]
	global_load_dwordx4 v[144:147], v[248:249], off
	global_load_dwordx4 v[148:151], v[248:249], off offset:256
	global_load_dwordx4 v[152:155], v[250:251], off
	global_load_dwordx4 v[156:159], v[250:251], off offset:256
	s_waitcnt vmcnt(10)
	s_barrier
	s_add_i32 s8, s1, 4
	s_lshl_b32 s96, s8, 13
	s_add_i32 m0, vcc_lo, 8192
	v_lshl_add_u64 v[160:161], v[188:189], 0, s[96:97]
	global_load_lds_dwordx4 v[160:161], off
	global_load_lds_dwordx4 v[160:161], off offset:1024
	ds_read_b128 v[196:199], v246 offset:16384
	ds_read_b128 v[200:203], v162 offset:16384
	ds_read_b128 v[204:207], v246 offset:18432
	ds_read_b128 v[242:245], v162 offset:18432
	s_add_i32 s8, s1, 4
	s_lshl_b32 s96, s8, 11
	v_lshl_add_u64 v[248:249], v[184:185], 0, s[96:97]
	v_lshl_add_u64 v[250:251], v[186:187], 0, s[96:97]
	s_waitcnt vmcnt(8) lgkmcnt(3)
	v_mfma_f32_16x16x32_bf16 v[112:115], v[196:199], v[128:131], v[112:115]
	v_mfma_f32_16x16x32_bf16 v[120:123], v[196:199], v[132:135], v[120:123]
	v_mfma_f32_16x16x32_bf16 v[80:83], v[196:199], v[136:139], v[80:83]
	v_mfma_f32_16x16x32_bf16 v[88:91], v[196:199], v[140:143], v[88:91]
	ds_read_b128 v[196:199], v246 offset:20480
	s_waitcnt lgkmcnt(3)
	v_mfma_f32_16x16x32_bf16 v[116:119], v[200:203], v[128:131], v[116:119]
	v_mfma_f32_16x16x32_bf16 v[124:127], v[200:203], v[132:135], v[124:127]
	v_mfma_f32_16x16x32_bf16 v[84:87], v[200:203], v[136:139], v[84:87]
	v_mfma_f32_16x16x32_bf16 v[92:95], v[200:203], v[140:143], v[92:95]
	ds_read_b128 v[200:203], v162 offset:20480
	s_waitcnt lgkmcnt(3)
	v_mfma_f32_16x16x32_bf16 v[96:99], v[204:207], v[128:131], v[96:99]
	v_mfma_f32_16x16x32_bf16 v[104:107], v[204:207], v[132:135], v[104:107]
	v_mfma_f32_16x16x32_bf16 v[64:67], v[204:207], v[136:139], v[64:67]
	v_mfma_f32_16x16x32_bf16 v[72:75], v[204:207], v[140:143], v[72:75]
	ds_read_b128 v[204:207], v246 offset:22528
	s_waitcnt lgkmcnt(3)
	v_mfma_f32_16x16x32_bf16 v[100:103], v[242:245], v[128:131], v[100:103]
	v_mfma_f32_16x16x32_bf16 v[108:111], v[242:245], v[132:135], v[108:111]
	v_mfma_f32_16x16x32_bf16 v[68:71], v[242:245], v[136:139], v[68:71]
	v_mfma_f32_16x16x32_bf16 v[76:79], v[242:245], v[140:143], v[76:79]
	ds_read_b128 v[242:245], v162 offset:22528
	s_waitcnt lgkmcnt(3)
	v_mfma_f32_16x16x32_bf16 v[48:51], v[196:199], v[128:131], v[48:51]
	v_mfma_f32_16x16x32_bf16 v[56:59], v[196:199], v[132:135], v[56:59]
	v_mfma_f32_16x16x32_bf16 v[16:19], v[196:199], v[136:139], v[16:19]
	v_mfma_f32_16x16x32_bf16 v[24:27], v[196:199], v[140:143], v[24:27]
	s_waitcnt lgkmcnt(2)
	v_mfma_f32_16x16x32_bf16 v[52:55], v[200:203], v[128:131], v[52:55]
	v_mfma_f32_16x16x32_bf16 v[60:63], v[200:203], v[132:135], v[60:63]
	v_mfma_f32_16x16x32_bf16 v[20:23], v[200:203], v[136:139], v[20:23]
	v_mfma_f32_16x16x32_bf16 v[28:31], v[200:203], v[140:143], v[28:31]
	s_waitcnt lgkmcnt(1)
	v_mfma_f32_16x16x32_bf16 v[32:35], v[204:207], v[128:131], v[32:35]
	v_mfma_f32_16x16x32_bf16 v[40:43], v[204:207], v[132:135], v[40:43]
	v_mfma_f32_16x16x32_bf16 v[0:3], v[204:207], v[136:139], v[0:3]
	v_mfma_f32_16x16x32_bf16 v[8:11], v[204:207], v[140:143], v[8:11]
	s_waitcnt lgkmcnt(0)
	v_mfma_f32_16x16x32_bf16 v[36:39], v[242:245], v[128:131], v[36:39]
	v_mfma_f32_16x16x32_bf16 v[44:47], v[242:245], v[132:135], v[44:47]
	v_mfma_f32_16x16x32_bf16 v[4:7], v[242:245], v[136:139], v[4:7]
	v_mfma_f32_16x16x32_bf16 v[12:15], v[242:245], v[140:143], v[12:15]
	global_load_dwordx4 v[128:131], v[248:249], off
	global_load_dwordx4 v[132:135], v[248:249], off offset:256
	global_load_dwordx4 v[136:139], v[250:251], off
	global_load_dwordx4 v[140:143], v[250:251], off offset:256
	s_waitcnt vmcnt(10)
	s_barrier
	s_add_i32 s8, s1, 5
	s_lshl_b32 s96, s8, 13
	s_add_i32 m0, vcc_lo, 16384
	v_lshl_add_u64 v[160:161], v[188:189], 0, s[96:97]
	global_load_lds_dwordx4 v[160:161], off
	global_load_lds_dwordx4 v[160:161], off offset:1024
	ds_read_b128 v[196:199], v246 offset:0
	ds_read_b128 v[200:203], v162 offset:0
	ds_read_b128 v[204:207], v246 offset:2048
	ds_read_b128 v[242:245], v162 offset:2048
	s_add_i32 s8, s1, 5
	s_lshl_b32 s96, s8, 11
	v_lshl_add_u64 v[248:249], v[184:185], 0, s[96:97]
	v_lshl_add_u64 v[250:251], v[186:187], 0, s[96:97]
	s_waitcnt vmcnt(8) lgkmcnt(3)
	v_mfma_f32_16x16x32_bf16 v[112:115], v[196:199], v[144:147], v[112:115]
	v_mfma_f32_16x16x32_bf16 v[120:123], v[196:199], v[148:151], v[120:123]
	v_mfma_f32_16x16x32_bf16 v[80:83], v[196:199], v[152:155], v[80:83]
	v_mfma_f32_16x16x32_bf16 v[88:91], v[196:199], v[156:159], v[88:91]
	ds_read_b128 v[196:199], v246 offset:4096
	s_waitcnt lgkmcnt(3)
	v_mfma_f32_16x16x32_bf16 v[116:119], v[200:203], v[144:147], v[116:119]
	v_mfma_f32_16x16x32_bf16 v[124:127], v[200:203], v[148:151], v[124:127]
	v_mfma_f32_16x16x32_bf16 v[84:87], v[200:203], v[152:155], v[84:87]
	v_mfma_f32_16x16x32_bf16 v[92:95], v[200:203], v[156:159], v[92:95]
	ds_read_b128 v[200:203], v162 offset:4096
	s_waitcnt lgkmcnt(3)
	v_mfma_f32_16x16x32_bf16 v[96:99], v[204:207], v[144:147], v[96:99]
	v_mfma_f32_16x16x32_bf16 v[104:107], v[204:207], v[148:151], v[104:107]
	v_mfma_f32_16x16x32_bf16 v[64:67], v[204:207], v[152:155], v[64:67]
	v_mfma_f32_16x16x32_bf16 v[72:75], v[204:207], v[156:159], v[72:75]
	ds_read_b128 v[204:207], v246 offset:6144
	s_waitcnt lgkmcnt(3)
	v_mfma_f32_16x16x32_bf16 v[100:103], v[242:245], v[144:147], v[100:103]
	v_mfma_f32_16x16x32_bf16 v[108:111], v[242:245], v[148:151], v[108:111]
	v_mfma_f32_16x16x32_bf16 v[68:71], v[242:245], v[152:155], v[68:71]
	v_mfma_f32_16x16x32_bf16 v[76:79], v[242:245], v[156:159], v[76:79]
	ds_read_b128 v[242:245], v162 offset:6144
	s_waitcnt lgkmcnt(3)
	v_mfma_f32_16x16x32_bf16 v[48:51], v[196:199], v[144:147], v[48:51]
	v_mfma_f32_16x16x32_bf16 v[56:59], v[196:199], v[148:151], v[56:59]
	v_mfma_f32_16x16x32_bf16 v[16:19], v[196:199], v[152:155], v[16:19]
	v_mfma_f32_16x16x32_bf16 v[24:27], v[196:199], v[156:159], v[24:27]
	s_waitcnt lgkmcnt(2)
	v_mfma_f32_16x16x32_bf16 v[52:55], v[200:203], v[144:147], v[52:55]
	v_mfma_f32_16x16x32_bf16 v[60:63], v[200:203], v[148:151], v[60:63]
	v_mfma_f32_16x16x32_bf16 v[20:23], v[200:203], v[152:155], v[20:23]
	v_mfma_f32_16x16x32_bf16 v[28:31], v[200:203], v[156:159], v[28:31]
	s_waitcnt lgkmcnt(1)
	v_mfma_f32_16x16x32_bf16 v[32:35], v[204:207], v[144:147], v[32:35]
	v_mfma_f32_16x16x32_bf16 v[40:43], v[204:207], v[148:151], v[40:43]
	v_mfma_f32_16x16x32_bf16 v[0:3], v[204:207], v[152:155], v[0:3]
	v_mfma_f32_16x16x32_bf16 v[8:11], v[204:207], v[156:159], v[8:11]
	s_waitcnt lgkmcnt(0)
	v_mfma_f32_16x16x32_bf16 v[36:39], v[242:245], v[144:147], v[36:39]
	v_mfma_f32_16x16x32_bf16 v[44:47], v[242:245], v[148:151], v[44:47]
	v_mfma_f32_16x16x32_bf16 v[4:7], v[242:245], v[152:155], v[4:7]
	v_mfma_f32_16x16x32_bf16 v[12:15], v[242:245], v[156:159], v[12:15]
	global_load_dwordx4 v[144:147], v[248:249], off
	global_load_dwordx4 v[148:151], v[248:249], off offset:256
	global_load_dwordx4 v[152:155], v[250:251], off
	global_load_dwordx4 v[156:159], v[250:251], off offset:256
	s_waitcnt vmcnt(10)
	s_barrier
	s_add_i32 s8, s1, 6
	s_lshl_b32 s96, s8, 13
	s_mov_b32 m0, vcc_lo
	v_lshl_add_u64 v[160:161], v[188:189], 0, s[96:97]
	global_load_lds_dwordx4 v[160:161], off
	global_load_lds_dwordx4 v[160:161], off offset:1024
	ds_read_b128 v[196:199], v246 offset:8192
	ds_read_b128 v[200:203], v162 offset:8192
	ds_read_b128 v[204:207], v246 offset:10240
	ds_read_b128 v[242:245], v162 offset:10240
	s_add_i32 s8, s1, 6
	s_lshl_b32 s96, s8, 11
	v_lshl_add_u64 v[248:249], v[184:185], 0, s[96:97]
	v_lshl_add_u64 v[250:251], v[186:187], 0, s[96:97]
	s_waitcnt vmcnt(8) lgkmcnt(3)
	v_mfma_f32_16x16x32_bf16 v[112:115], v[196:199], v[128:131], v[112:115]
	v_mfma_f32_16x16x32_bf16 v[120:123], v[196:199], v[132:135], v[120:123]
	v_mfma_f32_16x16x32_bf16 v[80:83], v[196:199], v[136:139], v[80:83]
	v_mfma_f32_16x16x32_bf16 v[88:91], v[196:199], v[140:143], v[88:91]
	ds_read_b128 v[196:199], v246 offset:12288
	s_waitcnt lgkmcnt(3)
	v_mfma_f32_16x16x32_bf16 v[116:119], v[200:203], v[128:131], v[116:119]
	v_mfma_f32_16x16x32_bf16 v[124:127], v[200:203], v[132:135], v[124:127]
	v_mfma_f32_16x16x32_bf16 v[84:87], v[200:203], v[136:139], v[84:87]
	v_mfma_f32_16x16x32_bf16 v[92:95], v[200:203], v[140:143], v[92:95]
	ds_read_b128 v[200:203], v162 offset:12288
	s_waitcnt lgkmcnt(3)
	v_mfma_f32_16x16x32_bf16 v[96:99], v[204:207], v[128:131], v[96:99]
	v_mfma_f32_16x16x32_bf16 v[104:107], v[204:207], v[132:135], v[104:107]
	v_mfma_f32_16x16x32_bf16 v[64:67], v[204:207], v[136:139], v[64:67]
	v_mfma_f32_16x16x32_bf16 v[72:75], v[204:207], v[140:143], v[72:75]
	ds_read_b128 v[204:207], v246 offset:14336
	s_waitcnt lgkmcnt(3)
	v_mfma_f32_16x16x32_bf16 v[100:103], v[242:245], v[128:131], v[100:103]
	v_mfma_f32_16x16x32_bf16 v[108:111], v[242:245], v[132:135], v[108:111]
	v_mfma_f32_16x16x32_bf16 v[68:71], v[242:245], v[136:139], v[68:71]
	v_mfma_f32_16x16x32_bf16 v[76:79], v[242:245], v[140:143], v[76:79]
	ds_read_b128 v[242:245], v162 offset:14336
	s_waitcnt lgkmcnt(3)
	v_mfma_f32_16x16x32_bf16 v[48:51], v[196:199], v[128:131], v[48:51]
	v_mfma_f32_16x16x32_bf16 v[56:59], v[196:199], v[132:135], v[56:59]
	v_mfma_f32_16x16x32_bf16 v[16:19], v[196:199], v[136:139], v[16:19]
	v_mfma_f32_16x16x32_bf16 v[24:27], v[196:199], v[140:143], v[24:27]
	s_waitcnt lgkmcnt(2)
	v_mfma_f32_16x16x32_bf16 v[52:55], v[200:203], v[128:131], v[52:55]
	v_mfma_f32_16x16x32_bf16 v[60:63], v[200:203], v[132:135], v[60:63]
	v_mfma_f32_16x16x32_bf16 v[20:23], v[200:203], v[136:139], v[20:23]
	v_mfma_f32_16x16x32_bf16 v[28:31], v[200:203], v[140:143], v[28:31]
	s_waitcnt lgkmcnt(1)
	v_mfma_f32_16x16x32_bf16 v[32:35], v[204:207], v[128:131], v[32:35]
	v_mfma_f32_16x16x32_bf16 v[40:43], v[204:207], v[132:135], v[40:43]
	v_mfma_f32_16x16x32_bf16 v[0:3], v[204:207], v[136:139], v[0:3]
	v_mfma_f32_16x16x32_bf16 v[8:11], v[204:207], v[140:143], v[8:11]
	s_waitcnt lgkmcnt(0)
	v_mfma_f32_16x16x32_bf16 v[36:39], v[242:245], v[128:131], v[36:39]
	v_mfma_f32_16x16x32_bf16 v[44:47], v[242:245], v[132:135], v[44:47]
	v_mfma_f32_16x16x32_bf16 v[4:7], v[242:245], v[136:139], v[4:7]
	v_mfma_f32_16x16x32_bf16 v[12:15], v[242:245], v[140:143], v[12:15]
	global_load_dwordx4 v[128:131], v[248:249], off
	global_load_dwordx4 v[132:135], v[248:249], off offset:256
	global_load_dwordx4 v[136:139], v[250:251], off
	global_load_dwordx4 v[140:143], v[250:251], off offset:256
	s_waitcnt vmcnt(10)
	s_barrier
	s_add_i32 s8, s1, 7
	s_lshl_b32 s96, s8, 13
	s_add_i32 m0, vcc_lo, 8192
	v_lshl_add_u64 v[160:161], v[188:189], 0, s[96:97]
	global_load_lds_dwordx4 v[160:161], off
	global_load_lds_dwordx4 v[160:161], off offset:1024
	ds_read_b128 v[196:199], v246 offset:16384
	ds_read_b128 v[200:203], v162 offset:16384
	ds_read_b128 v[204:207], v246 offset:18432
	ds_read_b128 v[242:245], v162 offset:18432
	s_add_i32 s8, s1, 7
	s_lshl_b32 s96, s8, 11
	v_lshl_add_u64 v[248:249], v[184:185], 0, s[96:97]
	v_lshl_add_u64 v[250:251], v[186:187], 0, s[96:97]
	s_waitcnt vmcnt(8) lgkmcnt(3)
	v_mfma_f32_16x16x32_bf16 v[112:115], v[196:199], v[144:147], v[112:115]
	v_mfma_f32_16x16x32_bf16 v[120:123], v[196:199], v[148:151], v[120:123]
	v_mfma_f32_16x16x32_bf16 v[80:83], v[196:199], v[152:155], v[80:83]
	v_mfma_f32_16x16x32_bf16 v[88:91], v[196:199], v[156:159], v[88:91]
	ds_read_b128 v[196:199], v246 offset:20480
	s_waitcnt lgkmcnt(3)
	v_mfma_f32_16x16x32_bf16 v[116:119], v[200:203], v[144:147], v[116:119]
	v_mfma_f32_16x16x32_bf16 v[124:127], v[200:203], v[148:151], v[124:127]
	v_mfma_f32_16x16x32_bf16 v[84:87], v[200:203], v[152:155], v[84:87]
	v_mfma_f32_16x16x32_bf16 v[92:95], v[200:203], v[156:159], v[92:95]
	ds_read_b128 v[200:203], v162 offset:20480
	s_waitcnt lgkmcnt(3)
	v_mfma_f32_16x16x32_bf16 v[96:99], v[204:207], v[144:147], v[96:99]
	v_mfma_f32_16x16x32_bf16 v[104:107], v[204:207], v[148:151], v[104:107]
	v_mfma_f32_16x16x32_bf16 v[64:67], v[204:207], v[152:155], v[64:67]
	v_mfma_f32_16x16x32_bf16 v[72:75], v[204:207], v[156:159], v[72:75]
	ds_read_b128 v[204:207], v246 offset:22528
	s_waitcnt lgkmcnt(3)
	v_mfma_f32_16x16x32_bf16 v[100:103], v[242:245], v[144:147], v[100:103]
	v_mfma_f32_16x16x32_bf16 v[108:111], v[242:245], v[148:151], v[108:111]
	v_mfma_f32_16x16x32_bf16 v[68:71], v[242:245], v[152:155], v[68:71]
	v_mfma_f32_16x16x32_bf16 v[76:79], v[242:245], v[156:159], v[76:79]
	ds_read_b128 v[242:245], v162 offset:22528
	s_waitcnt lgkmcnt(3)
	v_mfma_f32_16x16x32_bf16 v[48:51], v[196:199], v[144:147], v[48:51]
	v_mfma_f32_16x16x32_bf16 v[56:59], v[196:199], v[148:151], v[56:59]
	v_mfma_f32_16x16x32_bf16 v[16:19], v[196:199], v[152:155], v[16:19]
	v_mfma_f32_16x16x32_bf16 v[24:27], v[196:199], v[156:159], v[24:27]
	s_waitcnt lgkmcnt(2)
	v_mfma_f32_16x16x32_bf16 v[52:55], v[200:203], v[144:147], v[52:55]
	v_mfma_f32_16x16x32_bf16 v[60:63], v[200:203], v[148:151], v[60:63]
	v_mfma_f32_16x16x32_bf16 v[20:23], v[200:203], v[152:155], v[20:23]
	v_mfma_f32_16x16x32_bf16 v[28:31], v[200:203], v[156:159], v[28:31]
	s_waitcnt lgkmcnt(1)
	v_mfma_f32_16x16x32_bf16 v[32:35], v[204:207], v[144:147], v[32:35]
	v_mfma_f32_16x16x32_bf16 v[40:43], v[204:207], v[148:151], v[40:43]
	v_mfma_f32_16x16x32_bf16 v[0:3], v[204:207], v[152:155], v[0:3]
	v_mfma_f32_16x16x32_bf16 v[8:11], v[204:207], v[156:159], v[8:11]
	s_waitcnt lgkmcnt(0)
	v_mfma_f32_16x16x32_bf16 v[36:39], v[242:245], v[144:147], v[36:39]
	v_mfma_f32_16x16x32_bf16 v[44:47], v[242:245], v[148:151], v[44:47]
	v_mfma_f32_16x16x32_bf16 v[4:7], v[242:245], v[152:155], v[4:7]
	v_mfma_f32_16x16x32_bf16 v[12:15], v[242:245], v[156:159], v[12:15]
	global_load_dwordx4 v[144:147], v[248:249], off
	global_load_dwordx4 v[148:151], v[248:249], off offset:256
	global_load_dwordx4 v[152:155], v[250:251], off
	global_load_dwordx4 v[156:159], v[250:251], off offset:256
	s_waitcnt vmcnt(10)
	s_barrier
	s_add_i32 s1, s1, 6
	s_cmp_lt_u32 s1, 30
	s_cbranch_scc1 .Lg16_gu_k
	ds_read_b128 v[196:199], v246 offset:0
	ds_read_b128 v[200:203], v162 offset:0
	ds_read_b128 v[204:207], v246 offset:2048
	ds_read_b128 v[242:245], v162 offset:2048
	s_waitcnt vmcnt(6) lgkmcnt(3)
	v_mfma_f32_16x16x32_bf16 v[112:115], v[196:199], v[128:131], v[112:115]
	v_mfma_f32_16x16x32_bf16 v[120:123], v[196:199], v[132:135], v[120:123]
	v_mfma_f32_16x16x32_bf16 v[80:83], v[196:199], v[136:139], v[80:83]
	v_mfma_f32_16x16x32_bf16 v[88:91], v[196:199], v[140:143], v[88:91]
	ds_read_b128 v[196:199], v246 offset:4096
	s_waitcnt lgkmcnt(3)
	v_mfma_f32_16x16x32_bf16 v[116:119], v[200:203], v[128:131], v[116:119]
	v_mfma_f32_16x16x32_bf16 v[124:127], v[200:203], v[132:135], v[124:127]
	v_mfma_f32_16x16x32_bf16 v[84:87], v[200:203], v[136:139], v[84:87]
	v_mfma_f32_16x16x32_bf16 v[92:95], v[200:203], v[140:143], v[92:95]
	ds_read_b128 v[200:203], v162 offset:4096
	s_waitcnt lgkmcnt(3)
	v_mfma_f32_16x16x32_bf16 v[96:99], v[204:207], v[128:131], v[96:99]
	v_mfma_f32_16x16x32_bf16 v[104:107], v[204:207], v[132:135], v[104:107]
	v_mfma_f32_16x16x32_bf16 v[64:67], v[204:207], v[136:139], v[64:67]
	v_mfma_f32_16x16x32_bf16 v[72:75], v[204:207], v[140:143], v[72:75]
	ds_read_b128 v[204:207], v246 offset:6144
	s_waitcnt lgkmcnt(3)
	v_mfma_f32_16x16x32_bf16 v[100:103], v[242:245], v[128:131], v[100:103]
	v_mfma_f32_16x16x32_bf16 v[108:111], v[242:245], v[132:135], v[108:111]
	v_mfma_f32_16x16x32_bf16 v[68:71], v[242:245], v[136:139], v[68:71]
	v_mfma_f32_16x16x32_bf16 v[76:79], v[242:245], v[140:143], v[76:79]
	ds_read_b128 v[242:245], v162 offset:6144
	s_waitcnt lgkmcnt(3)
	v_mfma_f32_16x16x32_bf16 v[48:51], v[196:199], v[128:131], v[48:51]
	v_mfma_f32_16x16x32_bf16 v[56:59], v[196:199], v[132:135], v[56:59]
	v_mfma_f32_16x16x32_bf16 v[16:19], v[196:199], v[136:139], v[16:19]
	v_mfma_f32_16x16x32_bf16 v[24:27], v[196:199], v[140:143], v[24:27]
	s_waitcnt lgkmcnt(2)
	v_mfma_f32_16x16x32_bf16 v[52:55], v[200:203], v[128:131], v[52:55]
	v_mfma_f32_16x16x32_bf16 v[60:63], v[200:203], v[132:135], v[60:63]
	v_mfma_f32_16x16x32_bf16 v[20:23], v[200:203], v[136:139], v[20:23]
	v_mfma_f32_16x16x32_bf16 v[28:31], v[200:203], v[140:143], v[28:31]
	s_waitcnt lgkmcnt(1)
	v_mfma_f32_16x16x32_bf16 v[32:35], v[204:207], v[128:131], v[32:35]
	v_mfma_f32_16x16x32_bf16 v[40:43], v[204:207], v[132:135], v[40:43]
	v_mfma_f32_16x16x32_bf16 v[0:3], v[204:207], v[136:139], v[0:3]
	v_mfma_f32_16x16x32_bf16 v[8:11], v[204:207], v[140:143], v[8:11]
	s_waitcnt lgkmcnt(0)
	v_mfma_f32_16x16x32_bf16 v[36:39], v[242:245], v[128:131], v[36:39]
	v_mfma_f32_16x16x32_bf16 v[44:47], v[242:245], v[132:135], v[44:47]
	v_mfma_f32_16x16x32_bf16 v[4:7], v[242:245], v[136:139], v[4:7]
	v_mfma_f32_16x16x32_bf16 v[12:15], v[242:245], v[140:143], v[12:15]
	s_waitcnt vmcnt(4)
	s_barrier
	ds_read_b128 v[196:199], v246 offset:8192
	ds_read_b128 v[200:203], v162 offset:8192
	ds_read_b128 v[204:207], v246 offset:10240
	ds_read_b128 v[242:245], v162 offset:10240
	s_waitcnt vmcnt(0) lgkmcnt(3)
	v_mfma_f32_16x16x32_bf16 v[112:115], v[196:199], v[144:147], v[112:115]
	v_mfma_f32_16x16x32_bf16 v[120:123], v[196:199], v[148:151], v[120:123]
	v_mfma_f32_16x16x32_bf16 v[80:83], v[196:199], v[152:155], v[80:83]
	v_mfma_f32_16x16x32_bf16 v[88:91], v[196:199], v[156:159], v[88:91]
	ds_read_b128 v[196:199], v246 offset:12288
	s_waitcnt lgkmcnt(3)
	v_mfma_f32_16x16x32_bf16 v[116:119], v[200:203], v[144:147], v[116:119]
	v_mfma_f32_16x16x32_bf16 v[124:127], v[200:203], v[148:151], v[124:127]
	v_mfma_f32_16x16x32_bf16 v[84:87], v[200:203], v[152:155], v[84:87]
	v_mfma_f32_16x16x32_bf16 v[92:95], v[200:203], v[156:159], v[92:95]
	ds_read_b128 v[200:203], v162 offset:12288
	s_waitcnt lgkmcnt(3)
	v_mfma_f32_16x16x32_bf16 v[96:99], v[204:207], v[144:147], v[96:99]
	v_mfma_f32_16x16x32_bf16 v[104:107], v[204:207], v[148:151], v[104:107]
	v_mfma_f32_16x16x32_bf16 v[64:67], v[204:207], v[152:155], v[64:67]
	v_mfma_f32_16x16x32_bf16 v[72:75], v[204:207], v[156:159], v[72:75]
	ds_read_b128 v[204:207], v246 offset:14336
	s_waitcnt lgkmcnt(3)
	v_mfma_f32_16x16x32_bf16 v[100:103], v[242:245], v[144:147], v[100:103]
	v_mfma_f32_16x16x32_bf16 v[108:111], v[242:245], v[148:151], v[108:111]
	v_mfma_f32_16x16x32_bf16 v[68:71], v[242:245], v[152:155], v[68:71]
	v_mfma_f32_16x16x32_bf16 v[76:79], v[242:245], v[156:159], v[76:79]
	ds_read_b128 v[242:245], v162 offset:14336
	s_waitcnt lgkmcnt(3)
	v_mfma_f32_16x16x32_bf16 v[48:51], v[196:199], v[144:147], v[48:51]
	v_mfma_f32_16x16x32_bf16 v[56:59], v[196:199], v[148:151], v[56:59]
	v_mfma_f32_16x16x32_bf16 v[16:19], v[196:199], v[152:155], v[16:19]
	v_mfma_f32_16x16x32_bf16 v[24:27], v[196:199], v[156:159], v[24:27]
	s_waitcnt lgkmcnt(2)
	v_mfma_f32_16x16x32_bf16 v[52:55], v[200:203], v[144:147], v[52:55]
	v_mfma_f32_16x16x32_bf16 v[60:63], v[200:203], v[148:151], v[60:63]
	v_mfma_f32_16x16x32_bf16 v[20:23], v[200:203], v[152:155], v[20:23]
	v_mfma_f32_16x16x32_bf16 v[28:31], v[200:203], v[156:159], v[28:31]
	s_waitcnt lgkmcnt(1)
	v_mfma_f32_16x16x32_bf16 v[32:35], v[204:207], v[144:147], v[32:35]
	v_mfma_f32_16x16x32_bf16 v[40:43], v[204:207], v[148:151], v[40:43]
	v_mfma_f32_16x16x32_bf16 v[0:3], v[204:207], v[152:155], v[0:3]
	v_mfma_f32_16x16x32_bf16 v[8:11], v[204:207], v[156:159], v[8:11]
	s_waitcnt lgkmcnt(0)
	v_mfma_f32_16x16x32_bf16 v[36:39], v[242:245], v[144:147], v[36:39]
	v_mfma_f32_16x16x32_bf16 v[44:47], v[242:245], v[148:151], v[44:47]
	v_mfma_f32_16x16x32_bf16 v[4:7], v[242:245], v[152:155], v[4:7]
	v_mfma_f32_16x16x32_bf16 v[12:15], v[242:245], v[156:159], v[12:15]
	s_barrier
	s_nop 7
	s_nop 1
	s_waitcnt vmcnt(0)
	v_and_b32_e32 v128, 63, v179
	v_lshrrev_b32_e32 v129, 6, v179
	s_lshl_b32 s14, s7, 3
	s_mul_hi_u32 s15, s14, 0x2c000
	s_mul_i32 s14, s14, 0x2c000
	s_lshl_b32 s16, s0, 12
	s_add_u32 s12, s66, s14
	s_addc_u32 s13, s67, s15
	s_add_u32 s12, s12, s16
	s_addc_u32 s13, s13, 0
	v_and_b32_e32 v130, 15, v128
	v_lshlrev_b32_e32 v132, 4, v130
	v_lshrrev_b32_e32 v130, 4, v128
	v_lshl_add_u32 v132, v130, 9, v132
	v_mul_u32_u24_e32 v130, 0x58000, v129
	v_add_u32_e32 v132, v132, v130
	v_add_u32_e32 v133, 0x2c000, v132
	v_mul_f32_e32 v140, 0xbfb8aa3b, v112
	v_mul_f32_e32 v141, 0xbfb8aa3b, v113
	v_mul_f32_e32 v142, 0xbfb8aa3b, v114
	v_mul_f32_e32 v143, 0xbfb8aa3b, v115
	v_mul_f32_e32 v144, 0xbfb8aa3b, v116
	v_mul_f32_e32 v145, 0xbfb8aa3b, v117
	v_mul_f32_e32 v146, 0xbfb8aa3b, v118
	v_mul_f32_e32 v147, 0xbfb8aa3b, v119
	v_exp_f32_e32 v140, v140
	v_exp_f32_e32 v141, v141
	v_exp_f32_e32 v142, v142
	v_exp_f32_e32 v143, v143
	v_exp_f32_e32 v144, v144
	v_exp_f32_e32 v145, v145
	v_exp_f32_e32 v146, v146
	v_exp_f32_e32 v147, v147
	v_add_f32_e32 v140, 1.0, v140
	v_add_f32_e32 v141, 1.0, v141
	v_add_f32_e32 v142, 1.0, v142
	v_add_f32_e32 v143, 1.0, v143
	v_add_f32_e32 v144, 1.0, v144
	v_add_f32_e32 v145, 1.0, v145
	v_add_f32_e32 v146, 1.0, v146
	v_add_f32_e32 v147, 1.0, v147
	v_rcp_f32_e32 v140, v140
	v_rcp_f32_e32 v141, v141
	v_rcp_f32_e32 v142, v142
	v_rcp_f32_e32 v143, v143
	v_rcp_f32_e32 v144, v144
	v_rcp_f32_e32 v145, v145
	v_rcp_f32_e32 v146, v146
	v_rcp_f32_e32 v147, v147
	v_mul_f32_e32 v140, v112, v140
	v_mul_f32_e32 v141, v113, v141
	v_mul_f32_e32 v142, v114, v142
	v_mul_f32_e32 v143, v115, v143
	v_mul_f32_e32 v144, v116, v144
	v_mul_f32_e32 v145, v117, v145
	v_mul_f32_e32 v146, v118, v146
	v_mul_f32_e32 v147, v119, v147
	v_mul_f32_e32 v140, v96, v140
	v_mul_f32_e32 v141, v97, v141
	v_mul_f32_e32 v142, v98, v142
	v_mul_f32_e32 v143, v99, v143
	v_mul_f32_e32 v144, v100, v144
	v_mul_f32_e32 v145, v101, v145
	v_mul_f32_e32 v146, v102, v146
	v_mul_f32_e32 v147, v103, v147
	v_cvt_pk_bf16_f32 v148, v140, v141
	v_cvt_pk_bf16_f32 v149, v142, v143
	v_cvt_pk_bf16_f32 v150, v144, v145
	v_cvt_pk_bf16_f32 v151, v146, v147
	global_store_dwordx4 v132, v[148:151], s[12:13]
	v_mul_f32_e32 v140, 0xbfb8aa3b, v120
	v_mul_f32_e32 v141, 0xbfb8aa3b, v121
	v_mul_f32_e32 v142, 0xbfb8aa3b, v122
	v_mul_f32_e32 v143, 0xbfb8aa3b, v123
	v_mul_f32_e32 v144, 0xbfb8aa3b, v124
	v_mul_f32_e32 v145, 0xbfb8aa3b, v125
	v_mul_f32_e32 v146, 0xbfb8aa3b, v126
	v_mul_f32_e32 v147, 0xbfb8aa3b, v127
	v_exp_f32_e32 v140, v140
	v_exp_f32_e32 v141, v141
	v_exp_f32_e32 v142, v142
	v_exp_f32_e32 v143, v143
	v_exp_f32_e32 v144, v144
	v_exp_f32_e32 v145, v145
	v_exp_f32_e32 v146, v146
	v_exp_f32_e32 v147, v147
	v_add_f32_e32 v140, 1.0, v140
	v_add_f32_e32 v141, 1.0, v141
	v_add_f32_e32 v142, 1.0, v142
	v_add_f32_e32 v143, 1.0, v143
	v_add_f32_e32 v144, 1.0, v144
	v_add_f32_e32 v145, 1.0, v145
	v_add_f32_e32 v146, 1.0, v146
	v_add_f32_e32 v147, 1.0, v147
	v_rcp_f32_e32 v140, v140
	v_rcp_f32_e32 v141, v141
	v_rcp_f32_e32 v142, v142
	v_rcp_f32_e32 v143, v143
	v_rcp_f32_e32 v144, v144
	v_rcp_f32_e32 v145, v145
	v_rcp_f32_e32 v146, v146
	v_rcp_f32_e32 v147, v147
	v_mul_f32_e32 v140, v120, v140
	v_mul_f32_e32 v141, v121, v141
	v_mul_f32_e32 v142, v122, v142
	v_mul_f32_e32 v143, v123, v143
	v_mul_f32_e32 v144, v124, v144
	v_mul_f32_e32 v145, v125, v145
	v_mul_f32_e32 v146, v126, v146
	v_mul_f32_e32 v147, v127, v147
	v_mul_f32_e32 v140, v104, v140
	v_mul_f32_e32 v141, v105, v141
	v_mul_f32_e32 v142, v106, v142
	v_mul_f32_e32 v143, v107, v143
	v_mul_f32_e32 v144, v108, v144
	v_mul_f32_e32 v145, v109, v145
	v_mul_f32_e32 v146, v110, v146
	v_mul_f32_e32 v147, v111, v147
	v_cvt_pk_bf16_f32 v152, v140, v141
	v_cvt_pk_bf16_f32 v153, v142, v143
	v_cvt_pk_bf16_f32 v154, v144, v145
	v_cvt_pk_bf16_f32 v155, v146, v147
	global_store_dwordx4 v132, v[152:155], s[12:13] offset:256
	v_mul_f32_e32 v140, 0xbfb8aa3b, v80
	v_mul_f32_e32 v141, 0xbfb8aa3b, v81
	v_mul_f32_e32 v142, 0xbfb8aa3b, v82
	v_mul_f32_e32 v143, 0xbfb8aa3b, v83
	v_mul_f32_e32 v144, 0xbfb8aa3b, v84
	v_mul_f32_e32 v145, 0xbfb8aa3b, v85
	v_mul_f32_e32 v146, 0xbfb8aa3b, v86
	v_mul_f32_e32 v147, 0xbfb8aa3b, v87
	v_exp_f32_e32 v140, v140
	v_exp_f32_e32 v141, v141
	v_exp_f32_e32 v142, v142
	v_exp_f32_e32 v143, v143
	v_exp_f32_e32 v144, v144
	v_exp_f32_e32 v145, v145
	v_exp_f32_e32 v146, v146
	v_exp_f32_e32 v147, v147
	v_add_f32_e32 v140, 1.0, v140
	v_add_f32_e32 v141, 1.0, v141
	v_add_f32_e32 v142, 1.0, v142
	v_add_f32_e32 v143, 1.0, v143
	v_add_f32_e32 v144, 1.0, v144
	v_add_f32_e32 v145, 1.0, v145
	v_add_f32_e32 v146, 1.0, v146
	v_add_f32_e32 v147, 1.0, v147
	v_rcp_f32_e32 v140, v140
	v_rcp_f32_e32 v141, v141
	v_rcp_f32_e32 v142, v142
	v_rcp_f32_e32 v143, v143
	v_rcp_f32_e32 v144, v144
	v_rcp_f32_e32 v145, v145
	v_rcp_f32_e32 v146, v146
	v_rcp_f32_e32 v147, v147
	v_mul_f32_e32 v140, v80, v140
	v_mul_f32_e32 v141, v81, v141
	v_mul_f32_e32 v142, v82, v142
	v_mul_f32_e32 v143, v83, v143
	v_mul_f32_e32 v144, v84, v144
	v_mul_f32_e32 v145, v85, v145
	v_mul_f32_e32 v146, v86, v146
	v_mul_f32_e32 v147, v87, v147
	v_mul_f32_e32 v140, v64, v140
	v_mul_f32_e32 v141, v65, v141
	v_mul_f32_e32 v142, v66, v142
	v_mul_f32_e32 v143, v67, v143
	v_mul_f32_e32 v144, v68, v144
	v_mul_f32_e32 v145, v69, v145
	v_mul_f32_e32 v146, v70, v146
	v_mul_f32_e32 v147, v71, v147
	v_cvt_pk_bf16_f32 v156, v140, v141
	v_cvt_pk_bf16_f32 v157, v142, v143
	v_cvt_pk_bf16_f32 v158, v144, v145
	v_cvt_pk_bf16_f32 v159, v146, v147
	global_store_dwordx4 v133, v[156:159], s[12:13]
	v_mul_f32_e32 v140, 0xbfb8aa3b, v88
	v_mul_f32_e32 v141, 0xbfb8aa3b, v89
	v_mul_f32_e32 v142, 0xbfb8aa3b, v90
	v_mul_f32_e32 v143, 0xbfb8aa3b, v91
	v_mul_f32_e32 v144, 0xbfb8aa3b, v92
	v_mul_f32_e32 v145, 0xbfb8aa3b, v93
	v_mul_f32_e32 v146, 0xbfb8aa3b, v94
	v_mul_f32_e32 v147, 0xbfb8aa3b, v95
	v_exp_f32_e32 v140, v140
	v_exp_f32_e32 v141, v141
	v_exp_f32_e32 v142, v142
	v_exp_f32_e32 v143, v143
	v_exp_f32_e32 v144, v144
	v_exp_f32_e32 v145, v145
	v_exp_f32_e32 v146, v146
	v_exp_f32_e32 v147, v147
	v_add_f32_e32 v140, 1.0, v140
	v_add_f32_e32 v141, 1.0, v141
	v_add_f32_e32 v142, 1.0, v142
	v_add_f32_e32 v143, 1.0, v143
	v_add_f32_e32 v144, 1.0, v144
	v_add_f32_e32 v145, 1.0, v145
	v_add_f32_e32 v146, 1.0, v146
	v_add_f32_e32 v147, 1.0, v147
	v_rcp_f32_e32 v140, v140
	v_rcp_f32_e32 v141, v141
	v_rcp_f32_e32 v142, v142
	v_rcp_f32_e32 v143, v143
	v_rcp_f32_e32 v144, v144
	v_rcp_f32_e32 v145, v145
	v_rcp_f32_e32 v146, v146
	v_rcp_f32_e32 v147, v147
	v_mul_f32_e32 v140, v88, v140
	v_mul_f32_e32 v141, v89, v141
	v_mul_f32_e32 v142, v90, v142
	v_mul_f32_e32 v143, v91, v143
	v_mul_f32_e32 v144, v92, v144
	v_mul_f32_e32 v145, v93, v145
	v_mul_f32_e32 v146, v94, v146
	v_mul_f32_e32 v147, v95, v147
	v_mul_f32_e32 v140, v72, v140
	v_mul_f32_e32 v141, v73, v141
	v_mul_f32_e32 v142, v74, v142
	v_mul_f32_e32 v143, v75, v143
	v_mul_f32_e32 v144, v76, v144
	v_mul_f32_e32 v145, v77, v145
	v_mul_f32_e32 v146, v78, v146
	v_mul_f32_e32 v147, v79, v147
	v_cvt_pk_bf16_f32 v160, v140, v141
	v_cvt_pk_bf16_f32 v161, v142, v143
	v_cvt_pk_bf16_f32 v162, v144, v145
	v_cvt_pk_bf16_f32 v163, v146, v147
	global_store_dwordx4 v133, v[160:163], s[12:13] offset:256
	v_mul_f32_e32 v140, 0xbfb8aa3b, v48
	v_mul_f32_e32 v141, 0xbfb8aa3b, v49
	v_mul_f32_e32 v142, 0xbfb8aa3b, v50
	v_mul_f32_e32 v143, 0xbfb8aa3b, v51
	v_mul_f32_e32 v144, 0xbfb8aa3b, v52
	v_mul_f32_e32 v145, 0xbfb8aa3b, v53
	v_mul_f32_e32 v146, 0xbfb8aa3b, v54
	v_mul_f32_e32 v147, 0xbfb8aa3b, v55
	v_exp_f32_e32 v140, v140
	v_exp_f32_e32 v141, v141
	v_exp_f32_e32 v142, v142
	v_exp_f32_e32 v143, v143
	v_exp_f32_e32 v144, v144
	v_exp_f32_e32 v145, v145
	v_exp_f32_e32 v146, v146
	v_exp_f32_e32 v147, v147
	v_add_f32_e32 v140, 1.0, v140
	v_add_f32_e32 v141, 1.0, v141
	v_add_f32_e32 v142, 1.0, v142
	v_add_f32_e32 v143, 1.0, v143
	v_add_f32_e32 v144, 1.0, v144
	v_add_f32_e32 v145, 1.0, v145
	v_add_f32_e32 v146, 1.0, v146
	v_add_f32_e32 v147, 1.0, v147
	v_rcp_f32_e32 v140, v140
	v_rcp_f32_e32 v141, v141
	v_rcp_f32_e32 v142, v142
	v_rcp_f32_e32 v143, v143
	v_rcp_f32_e32 v144, v144
	v_rcp_f32_e32 v145, v145
	v_rcp_f32_e32 v146, v146
	v_rcp_f32_e32 v147, v147
	v_mul_f32_e32 v140, v48, v140
	v_mul_f32_e32 v141, v49, v141
	v_mul_f32_e32 v142, v50, v142
	v_mul_f32_e32 v143, v51, v143
	v_mul_f32_e32 v144, v52, v144
	v_mul_f32_e32 v145, v53, v145
	v_mul_f32_e32 v146, v54, v146
	v_mul_f32_e32 v147, v55, v147
	v_mul_f32_e32 v140, v32, v140
	v_mul_f32_e32 v141, v33, v141
	v_mul_f32_e32 v142, v34, v142
	v_mul_f32_e32 v143, v35, v143
	v_mul_f32_e32 v144, v36, v144
	v_mul_f32_e32 v145, v37, v145
	v_mul_f32_e32 v146, v38, v146
	v_mul_f32_e32 v147, v39, v147
	v_cvt_pk_bf16_f32 v148, v140, v141
	v_cvt_pk_bf16_f32 v149, v142, v143
	v_cvt_pk_bf16_f32 v150, v144, v145
	v_cvt_pk_bf16_f32 v151, v146, v147
	global_store_dwordx4 v132, v[148:151], s[12:13] offset:2048
	v_mul_f32_e32 v140, 0xbfb8aa3b, v56
	v_mul_f32_e32 v141, 0xbfb8aa3b, v57
	v_mul_f32_e32 v142, 0xbfb8aa3b, v58
	v_mul_f32_e32 v143, 0xbfb8aa3b, v59
	v_mul_f32_e32 v144, 0xbfb8aa3b, v60
	v_mul_f32_e32 v145, 0xbfb8aa3b, v61
	v_mul_f32_e32 v146, 0xbfb8aa3b, v62
	v_mul_f32_e32 v147, 0xbfb8aa3b, v63
	v_exp_f32_e32 v140, v140
	v_exp_f32_e32 v141, v141
	v_exp_f32_e32 v142, v142
	v_exp_f32_e32 v143, v143
	v_exp_f32_e32 v144, v144
	v_exp_f32_e32 v145, v145
	v_exp_f32_e32 v146, v146
	v_exp_f32_e32 v147, v147
	v_add_f32_e32 v140, 1.0, v140
	v_add_f32_e32 v141, 1.0, v141
	v_add_f32_e32 v142, 1.0, v142
	v_add_f32_e32 v143, 1.0, v143
	v_add_f32_e32 v144, 1.0, v144
	v_add_f32_e32 v145, 1.0, v145
	v_add_f32_e32 v146, 1.0, v146
	v_add_f32_e32 v147, 1.0, v147
	v_rcp_f32_e32 v140, v140
	v_rcp_f32_e32 v141, v141
	v_rcp_f32_e32 v142, v142
	v_rcp_f32_e32 v143, v143
	v_rcp_f32_e32 v144, v144
	v_rcp_f32_e32 v145, v145
	v_rcp_f32_e32 v146, v146
	v_rcp_f32_e32 v147, v147
	v_mul_f32_e32 v140, v56, v140
	v_mul_f32_e32 v141, v57, v141
	v_mul_f32_e32 v142, v58, v142
	v_mul_f32_e32 v143, v59, v143
	v_mul_f32_e32 v144, v60, v144
	v_mul_f32_e32 v145, v61, v145
	v_mul_f32_e32 v146, v62, v146
	v_mul_f32_e32 v147, v63, v147
	v_mul_f32_e32 v140, v40, v140
	v_mul_f32_e32 v141, v41, v141
	v_mul_f32_e32 v142, v42, v142
	v_mul_f32_e32 v143, v43, v143
	v_mul_f32_e32 v144, v44, v144
	v_mul_f32_e32 v145, v45, v145
	v_mul_f32_e32 v146, v46, v146
	v_mul_f32_e32 v147, v47, v147
	v_cvt_pk_bf16_f32 v152, v140, v141
	v_cvt_pk_bf16_f32 v153, v142, v143
	v_cvt_pk_bf16_f32 v154, v144, v145
	v_cvt_pk_bf16_f32 v155, v146, v147
	global_store_dwordx4 v132, v[152:155], s[12:13] offset:2304
	v_mul_f32_e32 v140, 0xbfb8aa3b, v16
	v_mul_f32_e32 v141, 0xbfb8aa3b, v17
	v_mul_f32_e32 v142, 0xbfb8aa3b, v18
	v_mul_f32_e32 v143, 0xbfb8aa3b, v19
	v_mul_f32_e32 v144, 0xbfb8aa3b, v20
	v_mul_f32_e32 v145, 0xbfb8aa3b, v21
	v_mul_f32_e32 v146, 0xbfb8aa3b, v22
	v_mul_f32_e32 v147, 0xbfb8aa3b, v23
	v_exp_f32_e32 v140, v140
	v_exp_f32_e32 v141, v141
	v_exp_f32_e32 v142, v142
	v_exp_f32_e32 v143, v143
	v_exp_f32_e32 v144, v144
	v_exp_f32_e32 v145, v145
	v_exp_f32_e32 v146, v146
	v_exp_f32_e32 v147, v147
	v_add_f32_e32 v140, 1.0, v140
	v_add_f32_e32 v141, 1.0, v141
	v_add_f32_e32 v142, 1.0, v142
	v_add_f32_e32 v143, 1.0, v143
	v_add_f32_e32 v144, 1.0, v144
	v_add_f32_e32 v145, 1.0, v145
	v_add_f32_e32 v146, 1.0, v146
	v_add_f32_e32 v147, 1.0, v147
	v_rcp_f32_e32 v140, v140
	v_rcp_f32_e32 v141, v141
	v_rcp_f32_e32 v142, v142
	v_rcp_f32_e32 v143, v143
	v_rcp_f32_e32 v144, v144
	v_rcp_f32_e32 v145, v145
	v_rcp_f32_e32 v146, v146
	v_rcp_f32_e32 v147, v147
	v_mul_f32_e32 v140, v16, v140
	v_mul_f32_e32 v141, v17, v141
	v_mul_f32_e32 v142, v18, v142
	v_mul_f32_e32 v143, v19, v143
	v_mul_f32_e32 v144, v20, v144
	v_mul_f32_e32 v145, v21, v145
	v_mul_f32_e32 v146, v22, v146
	v_mul_f32_e32 v147, v23, v147
	v_mul_f32_e32 v140, v0, v140
	v_mul_f32_e32 v141, v1, v141
	v_mul_f32_e32 v142, v2, v142
	v_mul_f32_e32 v143, v3, v143
	v_mul_f32_e32 v144, v4, v144
	v_mul_f32_e32 v145, v5, v145
	v_mul_f32_e32 v146, v6, v146
	v_mul_f32_e32 v147, v7, v147
	v_cvt_pk_bf16_f32 v156, v140, v141
	v_cvt_pk_bf16_f32 v157, v142, v143
	v_cvt_pk_bf16_f32 v158, v144, v145
	v_cvt_pk_bf16_f32 v159, v146, v147
	global_store_dwordx4 v133, v[156:159], s[12:13] offset:2048
	v_mul_f32_e32 v140, 0xbfb8aa3b, v24
	v_mul_f32_e32 v141, 0xbfb8aa3b, v25
	v_mul_f32_e32 v142, 0xbfb8aa3b, v26
	v_mul_f32_e32 v143, 0xbfb8aa3b, v27
	v_mul_f32_e32 v144, 0xbfb8aa3b, v28
	v_mul_f32_e32 v145, 0xbfb8aa3b, v29
	v_mul_f32_e32 v146, 0xbfb8aa3b, v30
	v_mul_f32_e32 v147, 0xbfb8aa3b, v31
	v_exp_f32_e32 v140, v140
	v_exp_f32_e32 v141, v141
	v_exp_f32_e32 v142, v142
	v_exp_f32_e32 v143, v143
	v_exp_f32_e32 v144, v144
	v_exp_f32_e32 v145, v145
	v_exp_f32_e32 v146, v146
	v_exp_f32_e32 v147, v147
	v_add_f32_e32 v140, 1.0, v140
	v_add_f32_e32 v141, 1.0, v141
	v_add_f32_e32 v142, 1.0, v142
	v_add_f32_e32 v143, 1.0, v143
	v_add_f32_e32 v144, 1.0, v144
	v_add_f32_e32 v145, 1.0, v145
	v_add_f32_e32 v146, 1.0, v146
	v_add_f32_e32 v147, 1.0, v147
	v_rcp_f32_e32 v140, v140
	v_rcp_f32_e32 v141, v141
	v_rcp_f32_e32 v142, v142
	v_rcp_f32_e32 v143, v143
	v_rcp_f32_e32 v144, v144
	v_rcp_f32_e32 v145, v145
	v_rcp_f32_e32 v146, v146
	v_rcp_f32_e32 v147, v147
	v_mul_f32_e32 v140, v24, v140
	v_mul_f32_e32 v141, v25, v141
	v_mul_f32_e32 v142, v26, v142
	v_mul_f32_e32 v143, v27, v143
	v_mul_f32_e32 v144, v28, v144
	v_mul_f32_e32 v145, v29, v145
	v_mul_f32_e32 v146, v30, v146
	v_mul_f32_e32 v147, v31, v147
	v_mul_f32_e32 v140, v8, v140
	v_mul_f32_e32 v141, v9, v141
	v_mul_f32_e32 v142, v10, v142
	v_mul_f32_e32 v143, v11, v143
	v_mul_f32_e32 v144, v12, v144
	v_mul_f32_e32 v145, v13, v145
	v_mul_f32_e32 v146, v14, v146
	v_mul_f32_e32 v147, v15, v147
	v_cvt_pk_bf16_f32 v160, v140, v141
	v_cvt_pk_bf16_f32 v161, v142, v143
	v_cvt_pk_bf16_f32 v162, v144, v145
	v_cvt_pk_bf16_f32 v163, v146, v147
	global_store_dwordx4 v133, v[160:163], s[12:13] offset:2304
	v_readlane_b32 s0, v254, 11
	s_add_i32 s2, s2, s0
	s_cmp_lt_i32 s2, s3
	s_barrier
	s_cbranch_scc1 .LBB0_1031
